# v14 + s_setprio 1/0 around the attention QK and PV MFMA bursts
# baseline (speedup 1.0000x reference)
; DI f32x16 mfma32(bf16x8 a, bf16x8 b, f32x16 c) { return __builtin_amdgcn_mfma_f32_32x32x16_bf16(a, b, c, 0, 0, 0); }
; template <int PM> DI void attn_phase(const Params& p, int l, char* smem, int* s_item, int wv, int cidx) {
;     ...
;         if (active) {
; #pragma unroll
;           for (int kb = 0; kb < 2; ++kb)
; #pragma unroll
;             for (int e = 0; e < 16; ++e) sacc[kb][e] = 0.f;
;           const char* Kc = Kb0 + cur * 17408 + l31 * 272 + dofs_b + h * 16;
;           bf16x8 kf[8];
;           if (full_d) {
; #pragma unroll
;             for (int j = 0; j < 8; ++j) kf[j] = *(const bf16x8*)(Kc + (j >> 3) * 32 * 272 + (j & 7) * 32);
; #pragma unroll
;             for (int j = 0; j < 16; ++j) {
;               sacc[j >> 3] = mfma32(kf[j & 7], qf[j & 7], sacc[j >> 3]);
;               if (j + 8 < 16) kf[j & 7] = *(const bf16x8*)(Kc + ((j + 8) >> 3) * 32 * 272 + ((j + 8) & 7) * 32);
;               __builtin_amdgcn_sched_barrier(0);
;             }
;           } else {
; #pragma unroll
;             for (int j = 0; j < 4; ++j) kf[j] = *(const bf16x8*)(Kc + (j >> 2) * 32 * 272 + (j & 3) * 32);
; #pragma unroll
;             for (int j = 0; j < 8; ++j) {
;               sacc[j >> 2] = mfma32(kf[j & 3], qf[j & 3], sacc[j >> 2]);
;               if (j + 4 < 8) kf[j & 3] = *(const bf16x8*)(Kc + ((j + 4) >> 2) * 32 * 272 + ((j + 4) & 3) * 32);
;               __builtin_amdgcn_sched_barrier(0);
;             }
;           }
.LBB0_435:
	v_cndmask_b32_e64 v0, 0, 1, s[2:3]
	v_cmp_ne_u32_e64 s[74:75], 1, v0
	s_andn2_b64 vcc, exec, s[2:3]
	s_mulk_i32 s95, 0x5000
	s_cbranch_vccnz .LBB0_441
	s_mulk_i32 s89, 0x4400
	v_add_u32_e32 v0, s89, v234
	ds_read_b128 v[48:51], v0
	ds_read_b128 v[10:13], v0 offset:32
	ds_read_b128 v[6:9], v0 offset:64
	ds_read_b128 v[2:5], v0 offset:96
	s_and_b64 vcc, exec, s[72:73]
	s_mov_b64 s[2:3], -1
	s_cbranch_vccnz .LBB0_438
	ds_read_b128 v[32:35], v0 offset:128
	ds_read_b128 v[36:39], v0 offset:160
	ds_read_b128 v[40:43], v0 offset:192
	ds_read_b128 v[44:47], v0 offset:224
	ds_read_b128 v[52:55], v0 offset:8704
	s_setprio 1
	s_waitcnt lgkmcnt(8)
	v_mfma_f32_32x32x16_bf16 v[16:31], v[48:51], v[148:151], 0
	s_waitcnt lgkmcnt(7)
	v_mfma_f32_32x32x16_bf16 v[16:31], v[10:13], v[152:155], v[16:31]
	ds_read_b128 v[56:59], v0 offset:8736
	s_waitcnt lgkmcnt(7)
	v_mfma_f32_32x32x16_bf16 v[16:31], v[6:9], v[156:159], v[16:31]
	ds_read_b128 v[60:63], v0 offset:8768
	s_waitcnt lgkmcnt(7)
	v_mfma_f32_32x32x16_bf16 v[16:31], v[2:5], v[160:163], v[16:31]
	ds_read_b128 v[64:67], v0 offset:8800
	s_waitcnt lgkmcnt(7)
	v_mfma_f32_32x32x16_bf16 v[16:31], v[32:35], v[164:167], v[16:31]
	ds_read_b128 v[68:71], v0 offset:8832
	s_waitcnt lgkmcnt(7)
	v_mfma_f32_32x32x16_bf16 v[16:31], v[36:39], v[168:171], v[16:31]
	ds_read_b128 v[72:75], v0 offset:8864
	s_waitcnt lgkmcnt(7)
	v_mfma_f32_32x32x16_bf16 v[16:31], v[40:43], v[172:175], v[16:31]
	ds_read_b128 v[76:79], v0 offset:8896
	s_waitcnt lgkmcnt(7)
	v_mfma_f32_32x32x16_bf16 v[16:31], v[44:47], v[176:179], v[16:31]
	ds_read_b128 v[144:147], v0 offset:8928
	s_waitcnt lgkmcnt(7)
	v_mfma_f32_32x32x16_bf16 v[32:47], v[52:55], v[148:151], 0
	s_waitcnt lgkmcnt(6)
	v_mfma_f32_32x32x16_bf16 v[32:47], v[56:59], v[152:155], v[32:47]
	s_waitcnt lgkmcnt(5)
	v_mfma_f32_32x32x16_bf16 v[32:47], v[60:63], v[156:159], v[32:47]
	s_waitcnt lgkmcnt(4)
	v_mfma_f32_32x32x16_bf16 v[32:47], v[64:67], v[160:163], v[32:47]
	s_waitcnt lgkmcnt(3)
	v_mfma_f32_32x32x16_bf16 v[32:47], v[68:71], v[164:167], v[32:47]
	s_waitcnt lgkmcnt(2)
	v_mfma_f32_32x32x16_bf16 v[32:47], v[72:75], v[168:171], v[32:47]
	s_waitcnt lgkmcnt(1)
	v_mfma_f32_32x32x16_bf16 v[32:47], v[76:79], v[172:175], v[32:47]
	s_waitcnt lgkmcnt(0)
	v_mfma_f32_32x32x16_bf16 v[32:47], v[144:147], v[176:179], v[32:47]
	s_setprio 0
	s_mov_b64 s[2:3], 0
.LBB0_438:
	s_andn2_b64 vcc, exec, s[2:3]
	s_cbranch_vccnz .LBB0_440
	s_setprio 1
	s_waitcnt lgkmcnt(3)
	v_mfma_f32_32x32x16_bf16 v[16:31], v[48:51], v[148:151], 0
	s_nop 6
	ds_read_b128 v[32:35], v0 offset:8704
	s_waitcnt lgkmcnt(3)
	v_mfma_f32_32x32x16_bf16 v[16:31], v[10:13], v[152:155], v[16:31]
	ds_read_b128 v[10:13], v0 offset:8736
	s_waitcnt lgkmcnt(3)
	v_mfma_f32_32x32x16_bf16 v[16:31], v[6:9], v[156:159], v[16:31]
	ds_read_b128 v[6:9], v0 offset:8768
	s_waitcnt lgkmcnt(3)
	v_mfma_f32_32x32x16_bf16 v[16:31], v[2:5], v[160:163], v[16:31]
	ds_read_b128 v[2:5], v0 offset:8800
	s_waitcnt lgkmcnt(3)
	v_mfma_f32_32x32x16_bf16 v[32:47], v[32:35], v[148:151], 0
	s_waitcnt lgkmcnt(2)
	v_mfma_f32_32x32x16_bf16 v[32:47], v[10:13], v[152:155], v[32:47]
	s_waitcnt lgkmcnt(1)
	v_mfma_f32_32x32x16_bf16 v[32:47], v[6:9], v[156:159], v[32:47]
	s_waitcnt lgkmcnt(0)
	v_mfma_f32_32x32x16_bf16 v[32:47], v[2:5], v[160:163], v[32:47]
	s_setprio 0

; DI unsigned pack2(float a, float b) { f2_t v = {a, b}; bf2_t r = __builtin_convertvector(v, bf2_t); return __builtin_bit_cast(unsigned, r); }
; DI float fexp2(float x) { return __builtin_amdgcn_exp2f(x); }
; template <int PM> DI void attn_phase(const Params& p, int l, char* smem, int* s_item, int wv, int cidx) {
;     ...
;           float ps = 0.f;
; #pragma unroll
;           for (int kb = 0; kb < 2; ++kb)
; #pragma unroll
;             for (int e = 0; e < 16; ++e) { const float pv = fexp2(sacc[kb][e] - m); sacc[kb][e] = pv; ps += pv; }
;           lsum += ps;
; #pragma unroll
;           for (int kb = 0; kb < 2; ++kb)
; #pragma unroll
;             for (int s2 = 0; s2 < 2; ++s2) {
;               u32x4 t;
;               t[0] = pack2(sacc[kb][8 * s2 + 0], sacc[kb][8 * s2 + 1]);
;               t[1] = pack2(sacc[kb][8 * s2 + 2], sacc[kb][8 * s2 + 3]);
;               t[2] = pack2(sacc[kb][8 * s2 + 4], sacc[kb][8 * s2 + 5]);
;               t[3] = pack2(sacc[kb][8 * s2 + 6], sacc[kb][8 * s2 + 7]);
;               pf[kb][s2] = __builtin_bit_cast(bf16x8, t);
;             }
;           if (!shift) ATT_PV_RUN(vcur); else pend = true;
.LBB0_514:
	v_sub_f32_e32 v2, v17, v233
	v_exp_f32_e32 v17, v2
	v_sub_f32_e32 v2, v18, v233
	v_exp_f32_e32 v18, v2
	v_sub_f32_e32 v2, v19, v233
	v_exp_f32_e32 v19, v2
	v_sub_f32_e32 v2, v20, v233
	v_sub_f32_e32 v0, v16, v233
	v_exp_f32_e32 v20, v2
	v_sub_f32_e32 v2, v21, v233
	v_exp_f32_e32 v16, v0
	v_exp_f32_e32 v21, v2
	v_sub_f32_e32 v2, v22, v233
	v_exp_f32_e32 v22, v2
	v_sub_f32_e32 v2, v23, v233
	v_exp_f32_e32 v23, v2
	v_sub_f32_e32 v2, v24, v233
	v_exp_f32_e32 v24, v2
	v_sub_f32_e32 v2, v25, v233
	v_add_f32_e32 v0, 0, v16
	v_exp_f32_e32 v25, v2
	v_sub_f32_e32 v2, v26, v233
	v_add_f32_e32 v0, v17, v0
	v_exp_f32_e32 v26, v2
	v_sub_f32_e32 v2, v27, v233
	v_add_f32_e32 v0, v18, v0
	v_exp_f32_e32 v27, v2
	v_sub_f32_e32 v2, v28, v233
	v_add_f32_e32 v0, v19, v0
	v_exp_f32_e32 v28, v2
	v_sub_f32_e32 v2, v29, v233
	v_add_f32_e32 v0, v20, v0
	v_exp_f32_e32 v29, v2
	v_sub_f32_e32 v2, v30, v233
	v_add_f32_e32 v0, v21, v0
	v_exp_f32_e32 v30, v2
	v_sub_f32_e32 v2, v31, v233
	v_add_f32_e32 v0, v22, v0
	v_exp_f32_e32 v31, v2
	v_sub_f32_e32 v2, v32, v233
	v_add_f32_e32 v0, v23, v0
	v_exp_f32_e32 v32, v2
	v_sub_f32_e32 v2, v33, v233
	v_add_f32_e32 v0, v24, v0
	v_exp_f32_e32 v33, v2
	v_sub_f32_e32 v2, v34, v233
	v_add_f32_e32 v0, v25, v0
	v_exp_f32_e32 v34, v2
	v_sub_f32_e32 v2, v35, v233
	v_add_f32_e32 v0, v26, v0
	v_exp_f32_e32 v35, v2
	v_sub_f32_e32 v2, v36, v233
	v_add_f32_e32 v0, v27, v0
	v_exp_f32_e32 v36, v2
	v_sub_f32_e32 v2, v37, v233
	v_add_f32_e32 v0, v28, v0
	v_exp_f32_e32 v37, v2
	v_sub_f32_e32 v2, v38, v233
	v_add_f32_e32 v0, v29, v0
	v_exp_f32_e32 v38, v2
	v_sub_f32_e32 v2, v39, v233
	v_add_f32_e32 v0, v30, v0
	v_exp_f32_e32 v39, v2
	v_sub_f32_e32 v2, v40, v233
	v_add_f32_e32 v0, v31, v0
	v_exp_f32_e32 v40, v2
	v_sub_f32_e32 v2, v41, v233
	v_add_f32_e32 v0, v32, v0
	v_exp_f32_e32 v41, v2
	v_sub_f32_e32 v2, v42, v233
	v_add_f32_e32 v0, v33, v0
	v_exp_f32_e32 v42, v2
	v_sub_f32_e32 v2, v43, v233
	v_add_f32_e32 v0, v34, v0
	v_exp_f32_e32 v43, v2
	v_sub_f32_e32 v2, v44, v233
	v_add_f32_e32 v0, v35, v0
	v_exp_f32_e32 v44, v2
	v_sub_f32_e32 v2, v45, v233
	v_add_f32_e32 v0, v36, v0
	v_exp_f32_e32 v45, v2
	v_sub_f32_e32 v2, v46, v233
	v_add_f32_e32 v0, v37, v0
	v_exp_f32_e32 v46, v2
	v_sub_f32_e32 v2, v47, v233
	v_add_u32_e32 v14, s95, v242
	v_add_f32_e32 v0, v38, v0
	v_exp_f32_e32 v47, v2
	v_cvt_pk_bf16_f32 v2, v16, v17
	v_cvt_pk_bf16_f32 v3, v18, v19
	v_cvt_pk_bf16_f32 v4, v20, v21
	v_cvt_pk_bf16_f32 v5, v22, v23
	ds_read_b64_tr_b16 v[52:53], v14 offset:39936
	ds_read_b64_tr_b16 v[54:55], v14 offset:42496
	ds_read_b64_tr_b16 v[56:57], v14 offset:45056
	ds_read_b64_tr_b16 v[58:59], v14 offset:47616
	ds_read_b64_tr_b16 v[60:61], v14 offset:50176
	ds_read_b64_tr_b16 v[62:63], v14 offset:52736
	v_add_f32_e32 v0, v39, v0
	s_waitcnt lgkmcnt(6)
	v_mfma_f32_32x32x16_bf16 v[128:143], v[144:147], v[2:5], v[128:143]
	v_add_f32_e32 v0, v40, v0
	v_add_f32_e32 v0, v41, v0
	v_add_f32_e32 v0, v42, v0
	ds_read_b64_tr_b16 v[64:65], v14 offset:34880
	ds_read_b64_tr_b16 v[66:67], v14 offset:37440
	v_add_f32_e32 v0, v43, v0
	v_add_f32_e32 v0, v44, v0
	v_add_f32_e32 v0, v45, v0
	v_add_f32_e32 v0, v46, v0
	v_add_f32_e32 v0, v47, v0
	v_cvt_pk_bf16_f32 v6, v24, v25
	v_cvt_pk_bf16_f32 v7, v26, v27
	v_cvt_pk_bf16_f32 v8, v28, v29
	v_cvt_pk_bf16_f32 v9, v30, v31
	v_cvt_pk_bf16_f32 v10, v32, v33
	v_cvt_pk_bf16_f32 v11, v34, v35
	v_cvt_pk_bf16_f32 v12, v36, v37
	v_cvt_pk_bf16_f32 v13, v38, v39
	v_cvt_pk_bf16_f32 v48, v40, v41
	v_cvt_pk_bf16_f32 v49, v42, v43
	v_cvt_pk_bf16_f32 v50, v44, v45
	v_cvt_pk_bf16_f32 v51, v46, v47
	s_setprio 1
	s_waitcnt lgkmcnt(6)
	v_mfma_f32_32x32x16_bf16 v[128:143], v[52:55], v[6:9], v[128:143]
	ds_read_b64_tr_b16 v[52:53], v14 offset:40000
	ds_read_b64_tr_b16 v[54:55], v14 offset:42560
	s_waitcnt lgkmcnt(6)
	v_mfma_f32_32x32x16_bf16 v[128:143], v[56:59], v[10:13], v[128:143]
	ds_read_b64_tr_b16 v[56:57], v14 offset:45120
	ds_read_b64_tr_b16 v[58:59], v14 offset:47680
	s_waitcnt lgkmcnt(6)
	v_mfma_f32_32x32x16_bf16 v[128:143], v[60:63], v[48:51], v[128:143]
	ds_read_b64_tr_b16 v[60:61], v14 offset:50240
	ds_read_b64_tr_b16 v[62:63], v14 offset:52800
	s_waitcnt lgkmcnt(6)
	v_mfma_f32_32x32x16_bf16 v[112:127], v[64:67], v[2:5], v[112:127]
	ds_read_b64_tr_b16 v[64:65], v14 offset:34944
	ds_read_b64_tr_b16 v[66:67], v14 offset:37504
	s_waitcnt lgkmcnt(6)
	v_mfma_f32_32x32x16_bf16 v[112:127], v[52:55], v[6:9], v[112:127]
	ds_read_b64_tr_b16 v[52:53], v14 offset:40064
	ds_read_b64_tr_b16 v[54:55], v14 offset:42624
	s_waitcnt lgkmcnt(6)
	v_mfma_f32_32x32x16_bf16 v[112:127], v[56:59], v[10:13], v[112:127]
	ds_read_b64_tr_b16 v[56:57], v14 offset:45184
	ds_read_b64_tr_b16 v[58:59], v14 offset:47744
	s_waitcnt lgkmcnt(6)
	v_mfma_f32_32x32x16_bf16 v[112:127], v[60:63], v[48:51], v[112:127]
	ds_read_b64_tr_b16 v[60:61], v14 offset:50304
	ds_read_b64_tr_b16 v[62:63], v14 offset:52864
	s_waitcnt lgkmcnt(6)
	v_mfma_f32_32x32x16_bf16 v[96:111], v[64:67], v[2:5], v[96:111]
	ds_read_b64_tr_b16 v[144:145], v14 offset:35008
	ds_read_b64_tr_b16 v[146:147], v14 offset:37568
	s_waitcnt lgkmcnt(6)
	v_mfma_f32_32x32x16_bf16 v[96:111], v[52:55], v[6:9], v[96:111]
	ds_read_b64_tr_b16 v[52:53], v14 offset:40128
	ds_read_b64_tr_b16 v[54:55], v14 offset:42688
	s_waitcnt lgkmcnt(6)
	v_mfma_f32_32x32x16_bf16 v[96:111], v[56:59], v[10:13], v[96:111]
	ds_read_b64_tr_b16 v[56:57], v14 offset:45248
	ds_read_b64_tr_b16 v[58:59], v14 offset:47808
	s_waitcnt lgkmcnt(6)
	v_mfma_f32_32x32x16_bf16 v[96:111], v[60:63], v[48:51], v[96:111]
	ds_read_b64_tr_b16 v[60:61], v14 offset:50368
	ds_read_b64_tr_b16 v[62:63], v14 offset:52928
	s_waitcnt lgkmcnt(6)
	v_mfma_f32_32x32x16_bf16 v[80:95], v[144:147], v[2:5], v[80:95]
	s_waitcnt lgkmcnt(4)
	v_mfma_f32_32x32x16_bf16 v[80:95], v[52:55], v[6:9], v[80:95]
	s_waitcnt lgkmcnt(2)
	v_mfma_f32_32x32x16_bf16 v[80:95], v[56:59], v[10:13], v[80:95]
	s_waitcnt lgkmcnt(0)
	v_mfma_f32_32x32x16_bf16 v[80:95], v[60:63], v[48:51], v[80:95]
	s_setprio 0
	v_add_f32_e32 v235, v235, v0
